# attn tile loop: fewer issue slots (DMA addr math in MFMA-result wait shadow, no m0 save/restore, redundant waitcnts, rowmax combine only on rescale)
# speedup vs baseline: 1.0393x; 1.0210x over previous
; #define SBAR() __builtin_amdgcn_sched_barrier(0)
; #define WAIT_BAR(N) asm volatile("s_waitcnt vmcnt(" #N ") lgkmcnt(0)\n\ts_barrier":::"memory")
; template<int THRL> __device__ __forceinline__ void attn_unit(int b,int h,int qb,const AttnArgs&A,char*shm,bool setup){
;     ...
;     WAIT_BAR(4);
;     const int kv0=t*KVBLK;
;     const bool act=(kv0<=qw0+QBLK-1);
;     const bool actn=(t+1<NT)&&(kv0+KVBLK<=qw0+QBLK-1);
;     const lds_cptr vp=vp0+vs_t;
;     const bool dk=(t+3<NT), dv=(t+2<NT);
;     const unsigned char*gk_=imgS+((size_t)(dk?t+3:NT-1)<<15); const unsigned char*gv_=imgS+((size_t)(dv?t+2:NT-1)<<15)+16384;
;     const unsigned kd_=(unsigned)__builtin_amdgcn_readfirstlane(dk?kdst+ks_t:ddst), vd_=(unsigned)__builtin_amdgcn_readfirstlane(dv?vdst+vs_nn:ddst);
;     if(act){
;       VRK(va,vp,0); VRK(vb,vp,1);
;       SBAR();
;       QKM(cini);
;     }
;     if(act){
;       const bool far=(qw0-(kv0+63)>=113);
;       if(!far){ const float*bt=biasT+mp*128; const int dq=qpos-kv0-4*hi;
;         #pragma unroll
;         for(int r=0;r<16;++r){ const int d=dq-((r&3)+8*(r>>2));
;           const int i0=d<0?0:(d>127?127:d);
;           const float b0=bt[i0];
;           const float n0=d>=0?0.f:-INFINITY;
;           p0[r]=(p0[r]+(b0-cfar))+n0; if((r&7)==7)asm volatile("":::"memory"); }
;         #pragma unroll
;         for(int r=0;r<16;++r){ const int d1=dq-32-((r&3)+8*(r>>2));
;           const int i1=d1<0?0:(d1>127?127:d1);
;           const float b1=bt[i1];
;           const float n1=d1>=0?0.f:-INFINITY;
;           p1[r]=(p1[r]+(b1-cfar))+n1; if((r&7)==7)asm volatile("":::"memory"); } }
;       const float rm=rowmax(p0,p1);
;       if(t==0||__any(rm>(float)THRL)){
;         const float dl=(t==0)?rm:__builtin_fmaxf(rm,0.f);
;         #pragma unroll
;         for(int r=0;r<16;++r){p0[r]-=dl;p1[r]-=dl;}
;         if(t>0){ const float f=__builtin_amdgcn_exp2f(-dl);
;           l*=f;
;           #pragma unroll
;           for(int d0=0;d0<4;++d0)
;             #pragma unroll
;             for(int r=0;r<16;++r)o[d0][r]*=f; }
;         mhat+=dl;
;         { const float ci=cfar-mhat;
;           #pragma unroll
;           for(int r=0;r<16;++r)cini[r]=ci;
;           asm volatile("":"+v"(cini)); }
.LBB0_243:
	s_add_i32 s95, s41, 1
	s_add_i32 s20, s73, s46
	s_cmp_lt_i32 s95, s72
	s_cselect_b32 s82, s20, s98
	s_add_i32 s20, s9, s99
	s_waitcnt vmcnt(4) lgkmcnt(0)
	s_barrier
	s_cmp_lt_i32 s41, s72
	s_cselect_b32 s73, s20, s98
	s_cmp_gt_i32 s40, s80
	s_cbranch_scc1 .Ltr_inact
	v_add_u32_e32 v15, s94, v210
	ds_read_b128 v[162:165], v15 offset:49152
	ds_read_b128 v[146:149], v15 offset:50176
	ds_read_b128 v[158:161], v15 offset:53248
	ds_read_b128 v[10:13], v15 offset:54272
	ds_read_b128 v[154:157], v15 offset:57344
	ds_read_b128 v[6:9], v15 offset:58368
	ds_read_b128 v[150:153], v15 offset:61440
	ds_read_b128 v[2:5], v15 offset:62464
	v_mfma_f32_32x32x16_bf16 v[114:129], v[178:181], v[130:133], v[82:97]
	s_cmpk_gt_i32 s22, 0x70
	v_mfma_f32_32x32x16_bf16 v[98:113], v[182:185], v[130:133], v[82:97]
	v_mfma_f32_32x32x16_bf16 v[98:113], v[186:189], v[134:137], v[98:113]
	v_mfma_f32_32x32x16_bf16 v[114:129], v[166:169], v[134:137], v[114:129]
	v_mfma_f32_32x32x16_bf16 v[98:113], v[190:193], v[138:141], v[98:113]
	v_mfma_f32_32x32x16_bf16 v[114:129], v[174:177], v[138:141], v[114:129]
	v_mfma_f32_32x32x16_bf16 v[98:113], v[194:197], v[142:145], v[98:113]
	v_mfma_f32_32x32x16_bf16 v[114:129], v[170:173], v[142:145], v[114:129]
	s_cbranch_scc1 .LBB0_246
	v_add_u32_e32 v212, s22, v14
	s_sub_i32 s20, s29, 0x18800
	s_lshl_b32 s20, s20, 1
	s_add_i32 s20, s20, 0x1d000
	v_lshl_add_u32 v213, v212, 2, s20
	ds_read_b32 v166, v213 offset:504
	ds_read_b32 v167, v213 offset:500
	ds_read_b32 v168, v213 offset:496
	ds_read_b32 v169, v213 offset:492
	ds_read_b32 v170, v213 offset:472
	ds_read_b32 v171, v213 offset:468
	ds_read_b32 v172, v213 offset:464
	ds_read_b32 v173, v213 offset:460
	ds_read_b32 v174, v213 offset:440
	ds_read_b32 v175, v213 offset:436
	ds_read_b32 v176, v213 offset:432
	ds_read_b32 v177, v213 offset:428
	ds_read_b32 v178, v213 offset:408
	ds_read_b32 v179, v213 offset:404
	ds_read_b32 v180, v213 offset:400
	ds_read_b32 v181, v213 offset:396
	ds_read_b32 v182, v213 offset:376
	ds_read_b32 v183, v213 offset:372
	ds_read_b32 v184, v213 offset:368
	ds_read_b32 v185, v213 offset:364
	ds_read_b32 v186, v213 offset:344
	ds_read_b32 v187, v213 offset:340
	ds_read_b32 v188, v213 offset:336
	ds_read_b32 v189, v213 offset:332
	ds_read_b32 v190, v213 offset:312
	ds_read_b32 v191, v213 offset:308
	ds_read_b32 v192, v213 offset:304
	ds_read_b32 v193, v213 offset:300
	ds_read_b32 v194, v213 offset:280
	ds_read_b32 v195, v213 offset:276
	ds_read_b32 v196, v213 offset:272
	ds_read_b32 v197, v213 offset:268
	s_waitcnt lgkmcnt(14)
	v_pk_add_f32 v[114:115], v[114:115], v[166:167]
	v_pk_add_f32 v[116:117], v[116:117], v[168:169]
	v_pk_add_f32 v[118:119], v[118:119], v[170:171]
	v_pk_add_f32 v[120:121], v[120:121], v[172:173]
	v_pk_add_f32 v[122:123], v[122:123], v[174:175]
	v_pk_add_f32 v[124:125], v[124:125], v[176:177]
	v_pk_add_f32 v[126:127], v[126:127], v[178:179]
	v_pk_add_f32 v[128:129], v[128:129], v[180:181]
	s_waitcnt lgkmcnt(0)
	v_pk_add_f32 v[98:99], v[98:99], v[182:183]
	v_pk_add_f32 v[100:101], v[100:101], v[184:185]
	v_pk_add_f32 v[102:103], v[102:103], v[186:187]
	v_pk_add_f32 v[104:105], v[104:105], v[188:189]
	v_pk_add_f32 v[106:107], v[106:107], v[190:191]
	v_pk_add_f32 v[108:109], v[108:109], v[192:193]
	v_pk_add_f32 v[110:111], v[110:111], v[194:195]
	v_pk_add_f32 v[112:113], v[112:113], v[196:197]
.LBB0_246:
	s_min_i32 s20, s95, s81
	s_lshl_b32 s20, s20, 15
	s_add_u32 s20, s42, s20
	s_addc_u32 s21, s43, 0
	s_min_i32 s84, s41, s81
	s_lshl_b32 s84, s84, 15
	s_add_u32 s84, s34, s84
	s_addc_u32 s85, s35, 0
	s_nop 1
	v_max_f32_e32 v166, v98, v99
	v_max3_f32 v166, v166, v100, v101
	v_max3_f32 v167, v114, v115, v116
	v_max3_f32 v166, v166, v102, v103
	v_max3_f32 v167, v167, v117, v118
	v_max3_f32 v166, v166, v104, v105
	v_max3_f32 v167, v167, v119, v120
	v_max3_f32 v166, v166, v106, v107
	v_max3_f32 v167, v167, v121, v122
	v_max3_f32 v166, v166, v108, v109
	v_max3_f32 v167, v167, v123, v124
	v_max3_f32 v166, v166, v110, v111
	v_max3_f32 v167, v167, v125, v126
	v_max3_f32 v166, v166, v112, v113
	v_max3_f32 v167, v167, v127, v128
	v_max3_f32 v166, v167, v129, v166
	v_cmp_lt_f32_e32 vcc, 0x41000000, v166
	s_cbranch_vccz .LBB0_248
	v_mov_b32_e32 v167, v166
	s_nop 1
	v_permlane32_swap_b32_e32 v166, v167
	s_nop 1
	v_max_f32_e32 v166, v166, v167
	v_max_f32_e32 v82, v166, v166
	v_max_f32_e32 v82, 0, v82
	v_exp_f32_e64 v84, -v82
	v_add_f32_e32 v0, v0, v82
	v_pk_add_f32 v[114:115], v[114:115], v[82:83] op_sel_hi:[1,0] neg_lo:[0,1] neg_hi:[0,1]
	v_pk_add_f32 v[98:99], v[98:99], v[82:83] op_sel_hi:[1,0] neg_lo:[0,1] neg_hi:[0,1]
	v_pk_add_f32 v[116:117], v[116:117], v[82:83] op_sel_hi:[1,0] neg_lo:[0,1] neg_hi:[0,1]
	v_pk_add_f32 v[100:101], v[100:101], v[82:83] op_sel_hi:[1,0] neg_lo:[0,1] neg_hi:[0,1]
	v_pk_add_f32 v[118:119], v[118:119], v[82:83] op_sel_hi:[1,0] neg_lo:[0,1] neg_hi:[0,1]
	v_pk_add_f32 v[102:103], v[102:103], v[82:83] op_sel_hi:[1,0] neg_lo:[0,1] neg_hi:[0,1]
	v_pk_add_f32 v[120:121], v[120:121], v[82:83] op_sel_hi:[1,0] neg_lo:[0,1] neg_hi:[0,1]
	v_pk_add_f32 v[104:105], v[104:105], v[82:83] op_sel_hi:[1,0] neg_lo:[0,1] neg_hi:[0,1]
	v_pk_add_f32 v[122:123], v[122:123], v[82:83] op_sel_hi:[1,0] neg_lo:[0,1] neg_hi:[0,1]
	v_pk_add_f32 v[106:107], v[106:107], v[82:83] op_sel_hi:[1,0] neg_lo:[0,1] neg_hi:[0,1]
	v_pk_add_f32 v[124:125], v[124:125], v[82:83] op_sel_hi:[1,0] neg_lo:[0,1] neg_hi:[0,1]
	v_pk_add_f32 v[108:109], v[108:109], v[82:83] op_sel_hi:[1,0] neg_lo:[0,1] neg_hi:[0,1]
	v_pk_add_f32 v[126:127], v[126:127], v[82:83] op_sel_hi:[1,0] neg_lo:[0,1] neg_hi:[0,1]
	v_pk_add_f32 v[110:111], v[110:111], v[82:83] op_sel_hi:[1,0] neg_lo:[0,1] neg_hi:[0,1]
; template<int THRL> __device__ __forceinline__ void attn_unit(int b,int h,int qb,const AttnArgs&A,char*shm,bool setup){
;     ...
;         const float dl=(t==0)?rm:__builtin_fmaxf(rm,0.f);
;         #pragma unroll
;         for(int r=0;r<16;++r){p0[r]-=dl;p1[r]-=dl;}
;         if(t>0){ const float f=__builtin_amdgcn_exp2f(-dl);
;           l*=f;
;           #pragma unroll
;           for(int d0=0;d0<4;++d0)
;             #pragma unroll
;             for(int r=0;r<16;++r)o[d0][r]*=f; }
;         mhat+=dl;
;         { const float ci=cfar-mhat;
;           #pragma unroll
;           for(int r=0;r<16;++r)cini[r]=ci;
;           asm volatile("":"+v"(cini)); }
	v_pk_add_f32 v[128:129], v[128:129], v[82:83] op_sel_hi:[1,0] neg_lo:[0,1] neg_hi:[0,1]
	v_pk_add_f32 v[112:113], v[112:113], v[82:83] op_sel_hi:[1,0] neg_lo:[0,1] neg_hi:[0,1]
	v_sub_f32_e32 v82, v64, v0
	v_mul_f32_e32 v211, v211, v84
	v_pk_mul_f32 v[30:31], v[30:31], v[84:85] op_sel_hi:[1,0]
	v_pk_mul_f32 v[28:29], v[28:29], v[84:85] op_sel_hi:[1,0]
	v_pk_mul_f32 v[26:27], v[26:27], v[84:85] op_sel_hi:[1,0]
	v_pk_mul_f32 v[24:25], v[24:25], v[84:85] op_sel_hi:[1,0]
	v_pk_mul_f32 v[22:23], v[22:23], v[84:85] op_sel_hi:[1,0]
	v_pk_mul_f32 v[20:21], v[20:21], v[84:85] op_sel_hi:[1,0]
	v_pk_mul_f32 v[18:19], v[18:19], v[84:85] op_sel_hi:[1,0]
	v_pk_mul_f32 v[16:17], v[16:17], v[84:85] op_sel_hi:[1,0]
	v_pk_mul_f32 v[46:47], v[46:47], v[84:85] op_sel_hi:[1,0]
	v_pk_mul_f32 v[44:45], v[44:45], v[84:85] op_sel_hi:[1,0]
	v_pk_mul_f32 v[42:43], v[42:43], v[84:85] op_sel_hi:[1,0]
	v_pk_mul_f32 v[40:41], v[40:41], v[84:85] op_sel_hi:[1,0]
	v_pk_mul_f32 v[38:39], v[38:39], v[84:85] op_sel_hi:[1,0]
	v_pk_mul_f32 v[36:37], v[36:37], v[84:85] op_sel_hi:[1,0]
	v_pk_mul_f32 v[34:35], v[34:35], v[84:85] op_sel_hi:[1,0]
	v_pk_mul_f32 v[32:33], v[32:33], v[84:85] op_sel_hi:[1,0]
	v_pk_mul_f32 v[62:63], v[62:63], v[84:85] op_sel_hi:[1,0]
	v_pk_mul_f32 v[60:61], v[60:61], v[84:85] op_sel_hi:[1,0]
	v_pk_mul_f32 v[58:59], v[58:59], v[84:85] op_sel_hi:[1,0]
	v_pk_mul_f32 v[56:57], v[56:57], v[84:85] op_sel_hi:[1,0]
	v_pk_mul_f32 v[54:55], v[54:55], v[84:85] op_sel_hi:[1,0]
	v_pk_mul_f32 v[52:53], v[52:53], v[84:85] op_sel_hi:[1,0]
	v_pk_mul_f32 v[50:51], v[50:51], v[84:85] op_sel_hi:[1,0]
	v_pk_mul_f32 v[48:49], v[48:49], v[84:85] op_sel_hi:[1,0]
	v_pk_mul_f32 v[80:81], v[80:81], v[84:85] op_sel_hi:[1,0]
	v_pk_mul_f32 v[78:79], v[78:79], v[84:85] op_sel_hi:[1,0]
	v_pk_mul_f32 v[76:77], v[76:77], v[84:85] op_sel_hi:[1,0]
	v_pk_mul_f32 v[74:75], v[74:75], v[84:85] op_sel_hi:[1,0]
	v_pk_mul_f32 v[72:73], v[72:73], v[84:85] op_sel_hi:[1,0]
	v_pk_mul_f32 v[70:71], v[70:71], v[84:85] op_sel_hi:[1,0]
	v_pk_mul_f32 v[68:69], v[68:69], v[84:85] op_sel_hi:[1,0]
	v_pk_mul_f32 v[66:67], v[66:67], v[84:85] op_sel_hi:[1,0]
	v_mov_b32_e32 v83, v82
	v_mov_b32_e32 v84, v82
	v_mov_b32_e32 v85, v82
	v_mov_b32_e32 v86, v82
	v_mov_b32_e32 v87, v82
	v_mov_b32_e32 v88, v82
	v_mov_b32_e32 v89, v82
	v_mov_b32_e32 v90, v82
	v_mov_b32_e32 v91, v82
	v_mov_b32_e32 v92, v82
	v_mov_b32_e32 v93, v82
	v_mov_b32_e32 v94, v82
	v_mov_b32_e32 v95, v82
	v_mov_b32_e32 v96, v82
	v_mov_b32_e32 v97, v82
; #define SBAR() __builtin_amdgcn_sched_barrier(0)
;   #define KRD(kp_) do{ _Pragma("unroll") for(int d0_=0;d0_<4;++d0_){ kf[2*d0_]=LDK(kp_,d0_*2048); kf[2*d0_+1]=LDK(kp_,d0_*2048+512); } }while(0)
;   #define VRK(dst,vp_,ks_) do{ _Pragma("unroll") for(int d0_=0;d0_<4;++d0_){ dst[d0_]=*(const __attribute__((address_space(3))) bf16x8*)((vp_)+d0_*4096+(ks_)*1024); } }while(0)
;       #define QTR(P,B,W,I) do{ EX2(P,B); asm volatile("":"+v"(sacc)); { unsigned w_=cvtpk_s(P[B],P[B+1]); asm volatile("":"+v"(w_)); W[I]=w_; } }while(0)
;       #define PV1(d0_,ks_,src) o[d0_]=__builtin_amdgcn_mfma_f32_32x32x16_bf16(src[d0_],__builtin_bit_cast(bf16x8,pw[ks_]),o[d0_],0,0,0)
; template<int THRL> __device__ __forceinline__ void attn_unit(int b,int h,int qb,const AttnArgs&A,char*shm,bool setup){
;     ...
;       float sacc=0.f;
;       QTR(p0,0,pw[0],0); QTR(p0,2,pw[0],1); QTR(p0,4,pw[0],2); QTR(p0,6,pw[0],3);
;       SBAR();
;       PV1(0,0,va); QTR(p0,8,pw[1],0);  SBAR();
;       PV1(1,0,va); QTR(p0,10,pw[1],1); SBAR();
;       PV1(2,0,va); QTR(p0,12,pw[1],2); SBAR();
;       PV1(3,0,va); QTR(p0,14,pw[1],3); SBAR();
;       VRK(va,vp,2); SBAR();
;       PV1(0,1,vb); QTR(p1,0,pw[2],0);  SBAR();
;       PV1(1,1,vb); QTR(p1,2,pw[2],1);  SBAR();
;       PV1(2,1,vb); QTR(p1,4,pw[2],2);  SBAR();
;       PV1(3,1,vb); QTR(p1,6,pw[2],3);  SBAR();
;       VRK(vb,vp,3); SBAR();
;       PV1(0,2,va); QTR(p1,8,pw[3],0);  SBAR();
;       PV1(1,2,va); QTR(p1,10,pw[3],1); SBAR();
;       PV1(2,2,va); QTR(p1,12,pw[3],2); SBAR();
;       PV1(3,2,va); QTR(p1,14,pw[3],3); SBAR();
;       KRD(kp0+ks_n); SBAR();
;       PV1(0,3,vb); PV1(1,3,vb); PV1(2,3,vb); PV1(3,3,vb);
;       l+=sacc;
;       SBAR();
;     ...
;     }
;     glds16s(gk_,voff,kd_); glds16s(gk_+8192,voff,kd_+8192); glds16s(gv_,voff,vd_); glds16s(gv_+8192,voff,vd_+8192);
;     ks_t=ks_n; ks_n=(ks_n==2*SLOT16)?0:ks_n+SLOT16; vs_t=(vs_t==2*SLOT16)?0:vs_t+SLOT16; vs_nn=(vs_nn==2*SLOT16)?0:vs_nn+SLOT16;
.LBB0_248:
	v_exp_f32_e32 v114, v114
	v_exp_f32_e32 v115, v115
	v_exp_f32_e32 v116, v116
	v_exp_f32_e32 v117, v117
	v_exp_f32_e32 v118, v118
	v_add_f32_e32 v166, v115, v114
	v_exp_f32_e32 v119, v119
	v_cvt_pk_bf16_f32 v114, v114, v115
	v_add_f32_e32 v115, v116, v166
	v_add_f32_e32 v166, v117, v115
	v_exp_f32_e32 v120, v120
	v_cvt_pk_bf16_f32 v115, v116, v117
	v_add_f32_e32 v116, v118, v166
	v_exp_f32_e32 v121, v121
	v_add_f32_e32 v117, v119, v116
	v_cvt_pk_bf16_f32 v116, v118, v119
	v_add_f32_e32 v117, v120, v117
	v_add_f32_e32 v118, v121, v117
	v_cvt_pk_bf16_f32 v117, v120, v121
	s_waitcnt lgkmcnt(0)
	s_nop 0
	v_mfma_f32_32x32x16_bf16 v[66:81], v[162:165], v[114:117], v[66:81]
	v_exp_f32_e32 v119, v122
	v_exp_f32_e32 v120, v123
	v_add_f32_e32 v118, v119, v118
	v_add_f32_e32 v121, v120, v118
	v_cvt_pk_bf16_f32 v118, v119, v120
	v_mfma_f32_32x32x16_bf16 v[48:63], v[158:161], v[114:117], v[48:63]
	v_exp_f32_e32 v119, v124
	v_exp_f32_e32 v120, v125
	v_add_f32_e32 v121, v119, v121
	v_add_f32_e32 v121, v120, v121
	v_cvt_pk_bf16_f32 v119, v119, v120
	v_mfma_f32_32x32x16_bf16 v[32:47], v[154:157], v[114:117], v[32:47]
	v_exp_f32_e32 v120, v126
	v_exp_f32_e32 v122, v127
	v_add_f32_e32 v121, v120, v121
	v_add_f32_e32 v121, v122, v121
	v_cvt_pk_bf16_f32 v120, v120, v122
	v_mfma_f32_32x32x16_bf16 v[16:31], v[150:153], v[114:117], v[16:31]
	v_exp_f32_e32 v114, v128
	v_exp_f32_e32 v115, v129
	v_add_f32_e32 v116, v114, v121
	v_add_f32_e32 v154, v115, v116
	v_cvt_pk_bf16_f32 v121, v114, v115
	ds_read_b128 v[122:125], v15 offset:51200
	ds_read_b128 v[126:129], v15 offset:55296
	ds_read_b128 v[150:153], v15 offset:59392
	ds_read_b128 v[114:117], v15 offset:63488
	v_mfma_f32_32x32x16_bf16 v[66:81], v[146:149], v[118:121], v[66:81]
	v_exp_f32_e32 v98, v98
	v_exp_f32_e32 v99, v99
	v_add_f32_e32 v146, v98, v154
	v_add_f32_e32 v146, v99, v146
	v_cvt_pk_bf16_f32 v98, v98, v99
	v_mfma_f32_32x32x16_bf16 v[48:63], v[10:13], v[118:121], v[48:63]
	v_exp_f32_e32 v10, v100
	v_exp_f32_e32 v11, v101
	v_add_f32_e32 v12, v10, v146
	v_add_f32_e32 v12, v11, v12
	v_cvt_pk_bf16_f32 v99, v10, v11
	v_mfma_f32_32x32x16_bf16 v[32:47], v[6:9], v[118:121], v[32:47]
	v_exp_f32_e32 v6, v102
	v_exp_f32_e32 v7, v103
	v_add_f32_e32 v8, v6, v12
	v_add_f32_e32 v8, v7, v8
	v_cvt_pk_bf16_f32 v100, v6, v7
	v_mfma_f32_32x32x16_bf16 v[16:31], v[2:5], v[118:121], v[16:31]
	v_exp_f32_e32 v2, v104
	v_exp_f32_e32 v3, v105
	v_add_f32_e32 v4, v2, v8
	v_add_f32_e32 v118, v3, v4
	v_cvt_pk_bf16_f32 v101, v2, v3
	ds_read_b128 v[2:5], v15 offset:52224
	ds_read_b128 v[6:9], v15 offset:56320
	ds_read_b128 v[10:13], v15 offset:60416
	ds_read_b128 v[102:105], v15 offset:64512
	s_waitcnt lgkmcnt(7)
	v_mfma_f32_32x32x16_bf16 v[66:81], v[122:125], v[98:101], v[66:81]
	v_exp_f32_e32 v15, v106
	v_exp_f32_e32 v106, v107
	v_add_f32_e32 v107, v15, v118
	v_add_f32_e32 v107, v106, v107
	v_cvt_pk_bf16_f32 v106, v15, v106
	s_waitcnt lgkmcnt(6)
	v_mfma_f32_32x32x16_bf16 v[48:63], v[126:129], v[98:101], v[48:63]
	v_exp_f32_e32 v15, v108
	v_exp_f32_e32 v108, v109
	v_add_f32_e32 v107, v15, v107
	v_add_f32_e32 v109, v108, v107
	v_cvt_pk_bf16_f32 v107, v15, v108
	s_waitcnt lgkmcnt(5)
	v_mfma_f32_32x32x16_bf16 v[32:47], v[150:153], v[98:101], v[32:47]
	v_exp_f32_e32 v15, v110
	v_exp_f32_e32 v108, v111
	v_add_f32_e32 v109, v15, v109
	v_add_f32_e32 v109, v108, v109
	v_cvt_pk_bf16_f32 v108, v15, v108
	s_waitcnt lgkmcnt(4)
	v_mfma_f32_32x32x16_bf16 v[16:31], v[114:117], v[98:101], v[16:31]
	v_exp_f32_e32 v15, v112
	v_exp_f32_e32 v98, v113
	v_add_f32_e32 v99, v15, v109
	v_add_f32_e32 v99, v98, v99
	v_cvt_pk_bf16_f32 v109, v15, v98
	v_add_u32_e32 v15, s23, v65
	ds_read_b128 v[178:181], v15
	ds_read_b128 v[182:185], v15 offset:512
	ds_read_b128 v[166:169], v15 offset:2048
	ds_read_b128 v[186:189], v15 offset:2560
	ds_read_b128 v[174:177], v15 offset:4096
	ds_read_b128 v[190:193], v15 offset:4608
	ds_read_b128 v[170:173], v15 offset:6144
	ds_read_b128 v[194:197], v15 offset:6656
	s_waitcnt lgkmcnt(11)
	v_mfma_f32_32x32x16_bf16 v[66:81], v[2:5], v[106:109], v[66:81]
	v_add_f32_e32 v211, v211, v99
	s_waitcnt lgkmcnt(10)
	v_mfma_f32_32x32x16_bf16 v[48:63], v[6:9], v[106:109], v[48:63]
	s_waitcnt lgkmcnt(9)
	v_mfma_f32_32x32x16_bf16 v[32:47], v[10:13], v[106:109], v[32:47]
	s_waitcnt lgkmcnt(8)
	v_mfma_f32_32x32x16_bf16 v[16:31], v[102:105], v[106:109], v[16:31]
.LBB0_249:
	s_mov_b32 m0, s82
	s_add_i32 s83, s82, 0x2000
	global_load_lds_dwordx4 v209, s[20:21]
	s_add_u32 s20, s20, 0x2000
	s_addc_u32 s21, s21, 0
	s_mov_b32 m0, s83
	s_nop 0
	global_load_lds_dwordx4 v209, s[20:21]
	s_mov_b32 m0, s73
	s_add_i32 s83, s73, 0x2000
	global_load_lds_dwordx4 v209, s[84:85]
	s_add_u32 s84, s84, 0x2000
	s_addc_u32 s85, s85, 0
	s_mov_b32 m0, s83
	s_add_i32 s73, s23, 0x4000
	global_load_lds_dwordx4 v209, s[84:85]
	s_cmpk_lg_u32 s23, 0x8000
	s_cselect_b32 s82, s73, 0
	s_add_i32 s73, s94, 0x4000
	s_cmpk_lg_u32 s94, 0x8000
	s_cselect_b32 s94, s73, 0
	s_add_i32 s73, s9, 0x4000
	s_cmpk_lg_u32 s9, 0x8000
	s_cselect_b32 s9, s73, 0
	s_add_i32 s73, s8, s95
	s_sub_i32 s22, s22, 64
	s_add_i32 s40, s40, 64
	s_cmp_eq_u32 s73, 2
	s_cbranch_scc1 .LBB0_252
	s_mov_b32 s41, s95
	s_mov_b32 s73, s23
	s_mov_b32 s23, s82
	s_branch .LBB0_243
.Ltr_inact:
	s_min_i32 s20, s95, s81
	s_lshl_b32 s20, s20, 15
	s_add_u32 s20, s42, s20
	s_addc_u32 s21, s43, 0
	s_min_i32 s84, s41, s81
	s_lshl_b32 s84, s84, 15
	s_add_u32 s84, s34, s84
	s_addc_u32 s85, s35, 0
	s_branch .LBB0_249
